# baseline (speedup 1.0000x reference)
; __device__ __forceinline__ void phase0_misc(unsigned char* ws, int wv_) {
;     ...
;     for (int i = gtid; i < 6400 * 64; i += gsz) {
;       int r = i % 6400, kc = i / 6400;
;       int grp = r / BW_, c = r - grp * BW_;
;       float f[8];
; #pragma unroll
;       for (int e = 0; e < 8; ++e) {
;         int kcol = kc * 8 + e;
;         float v = 0.f;
;         if (grp < 2) { int l = kcol - grp * 64; if (l >= 0 && l < 64) v = w2[((size_t)grp * 64 + l) * BW_ + c]; }
;         else if (grp < 4) { int l = kcol - 128 - (grp - 2) * 64; if (l >= 0 && l < 64) v = a2[((size_t)(grp - 2) * 64 + l) * BW_ + c]; }
;         else { int l = kcol - 256; if (l >= 0 && l < 192) v = g2[(size_t)l * BW_ + c]; }
;         f[e] = v;
;       }
;       *(uint4*)(wl + (size_t)((r & ~255) + perm256(r & 255)) * 512 + kc * 8) = pack8(f);
;     }
.LBB0_40:
	s_waitcnt lgkmcnt(0)
	v_mul_hi_i32 v2, v6, s15
	v_lshrrev_b32_e32 v4, 31, v2
	v_ashrrev_i32_e32 v2, 11, v2
	v_add_u32_e32 v15, v2, v4
	v_mul_i32_i24_e32 v2, 0x1900, v15
	v_sub_u32_e32 v5, v6, v2
	v_lshrrev_b32_e32 v14, 8, v5
	v_mul_u32_u24_e32 v14, 13, v14
	v_lshrrev_b32_e32 v14, 6, v14
	v_mul_u32_u24_e32 v2, 0x500, v14
	v_sub_u32_e32 v10, v5, v2
	v_lshlrev_b32_e32 v2, 3, v14
	v_sub_u32_e32 v16, v15, v2
	v_mov_b32_e32 v18, 24
	v_cmp_eq_u32_e32 vcc, 4, v14
	v_and_b32_e32 v2, 1, v14
	v_lshlrev_b32_e32 v2, 6, v2
	v_cndmask_b32_e32 v17, 8, v18, vcc
	v_cndmask_b32_e32 v2, v2, v3, vcc
	v_lshl_add_u32 v19, v16, 3, v2
	v_mul_u32_u24_e32 v19, 0x500, v19
	v_add_u32_e32 v19, v19, v10
	v_lshlrev_b32_e32 v70, 2, v19
	v_mov_b32_e32 v71, 0
	v_mov_b32_e32 v20, s18
	v_mov_b32_e32 v21, s19
	v_cmp_lt_u32_e32 vcc, 1, v14
	v_mov_b32_e32 v2, s8
	v_mov_b32_e32 v4, s9
	v_cndmask_b32_e32 v20, v20, v2, vcc
	v_cndmask_b32_e32 v21, v21, v4, vcc
	v_cmp_eq_u32_e32 vcc, 4, v14
	v_mov_b32_e32 v2, s10
	v_mov_b32_e32 v4, s11
	v_cndmask_b32_e32 v20, v20, v2, vcc
	v_cndmask_b32_e32 v21, v21, v4, vcc
	v_lshl_add_u64 v[72:73], v[20:21], 0, v[70:71]
	v_mov_b32_e32 v22, 0
	v_mov_b32_e32 v23, 0
	v_mov_b32_e32 v24, 0
	v_mov_b32_e32 v25, 0
	v_mov_b32_e32 v26, 0
	v_mov_b32_e32 v27, 0
	v_mov_b32_e32 v28, 0
	v_mov_b32_e32 v29, 0
	v_cmp_lt_u32_e32 vcc, v16, v17
	s_and_saveexec_b64 s[4:5], vcc
	s_cbranch_execz .Llw_skip
	s_mov_b64 s[22:23], 0x1400
	global_load_dword v22, v[72:73], off
	v_lshl_add_u64 v[72:73], v[72:73], 0, s[22:23]
	global_load_dword v23, v[72:73], off
	v_lshl_add_u64 v[72:73], v[72:73], 0, s[22:23]
	global_load_dword v24, v[72:73], off
	v_lshl_add_u64 v[72:73], v[72:73], 0, s[22:23]
	global_load_dword v25, v[72:73], off
	v_lshl_add_u64 v[72:73], v[72:73], 0, s[22:23]
	global_load_dword v26, v[72:73], off
	v_lshl_add_u64 v[72:73], v[72:73], 0, s[22:23]
	global_load_dword v27, v[72:73], off
	v_lshl_add_u64 v[72:73], v[72:73], 0, s[22:23]
	global_load_dword v28, v[72:73], off
	v_lshl_add_u64 v[72:73], v[72:73], 0, s[22:23]
	global_load_dword v29, v[72:73], off
.Llw_skip:
	s_or_b64 exec, exec, s[4:5]
	v_lshrrev_b32_e32 v74, 1, v5
	v_and_b32_e32 v75, 0xffffff00, v5
	v_lshlrev_b32_e32 v76, 6, v5
	v_and_b32_e32 v74, 0x60, v74
	v_lshlrev_b32_e32 v77, 4, v5
	v_bfe_u32 v78, v5, 2, 4
	v_and_b32_e32 v76, 0x80, v76
	v_and_b32_e32 v77, 16, v77
	v_or3_b32 v74, v74, v75, v78
	v_or3_b32 v74, v74, v76, v77
	v_mov_b32_e32 v75, 0
	v_readlane_b32 s4, v251, 9
	v_lshlrev_b64 v[74:75], 10, v[74:75]
	v_readlane_b32 s5, v251, 10
	v_lshlrev_b32_e32 v76, 4, v15
	v_mov_b32_e32 v77, 0
	s_nop 1
	v_lshl_add_u64 v[74:75], s[4:5], 0, v[74:75]
	v_lshl_add_u64 v[74:75], v[74:75], 0, v[76:77]
	s_waitcnt vmcnt(0)
	v_cvt_pk_bf16_f32 v8, v22, v23
	v_cvt_pk_bf16_f32 v9, v24, v25
	v_cvt_pk_bf16_f32 v10, v26, v27
	v_cvt_pk_bf16_f32 v11, v28, v29
	global_store_dwordx4 v[74:75], v[8:11], off
	v_add_u32_e32 v6, s14, v6
	v_cmp_lt_i32_e32 vcc, s36, v6
	s_or_b64 s[20:21], vcc, s[20:21]
	s_andn2_b64 exec, exec, s[20:21]
	s_cbranch_execnz .LBB0_40
